# ret_local chunk-top touches for the end-of-chunk loads; EpiResid0 epilogue stores write-through (sc1)
# baseline (speedup 1.0000x reference)
;     __device__ __forceinline__ void operator()(const f32x4 (&acc)[2][2][4][2], const pg8::Unit& u, int wr, int wc, int fr, int fq) const {
;         const int col0 = u.pn * 256 + wc * 32 + 8 * fq;
;         const bool wr_hb = (MODE == 0) || (hb != nullptr);
; #pragma unroll
;         for (int ai = 0; ai < 2; ++ai)
; #pragma unroll
;             for (int m = 0; m < 4; ++m) {
;                 const int row = u.pm * 256 + ai * 128 + wr * 64 + m * 16 + fr;
;                 const size_t off = (size_t)row * DM + col0;
;                 bf16_t* hrow = (hb_hi && row >= HALF_TOK) ? hb_hi + (size_t)(row - HALF_TOK) * DM + col0 : hb + off;
;                 float rs = 0.f, part = 0.f;
;                 if (MODE == 1) rs = rsqrtf(ssq_in[row] * (1.f / DM) + EPS);
; #pragma unroll
;                 for (int bj = 0; bj < 2; ++bj) {
;                     const size_t o = off + bj * 128;
;                     const f32x4 bs0 = *(const f32x4*)(base + o), bs1 = *(const f32x4*)(base + o + 4);
;                     f32x4 a0 = acc[ai][bj][m][0], a1 = acc[ai][bj][m][1];
;                     if (MODE == 1) {
;                         const u32x4 pw = *(const u32x4*)(pp + o);
;                         a0[0] = bflo(pw.x) * sigmoidf_(rs * a0[0]); a0[1] = bfhi(pw.x) * sigmoidf_(rs * a0[1]);
;                         a0[2] = bflo(pw.y) * sigmoidf_(rs * a0[2]); a0[3] = bfhi(pw.y) * sigmoidf_(rs * a0[3]);
;                         a1[0] = bflo(pw.z) * sigmoidf_(rs * a1[0]); a1[1] = bfhi(pw.z) * sigmoidf_(rs * a1[1]);
;                         a1[2] = bflo(pw.w) * sigmoidf_(rs * a1[2]); a1[3] = bfhi(pw.w) * sigmoidf_(rs * a1[3]);
;                     }
;                     const f32x4 v0 = bs0 + a0, v1 = bs1 + a1;
;                     *(f32x4*)(out + o) = v0; *(f32x4*)(out + o + 4) = v1;
;                     if (wr_hb) {
;                         const u32x2 h0 = pack4(v0), h1 = pack4(v1); const u32x4 hw = {h0.x, h0.y, h1.x, h1.y};
;                         *(u32x4*)(hrow + bj * 128) = hw;
;                         part += ((v0[0] * v0[0] + v0[1] * v0[1]) + (v0[2] * v0[2] + v0[3] * v0[3])) + ((v1[0] * v1[0] + v1[1] * v1[1]) + (v1[2] * v1[2] + v1[3] * v1[3]));
;                     }
;                 }
;                 if (wr_hb) { part += __shfl_xor(part, 16); part += __shfl_xor(part, 32); if (fq == 0) unsafeAtomicAdd(ssq_out + row, part); }
.LBB0_471:
	v_lshl_add_u32 v138, s67, 8, v142
	v_lshl_or_b32 v140, s66, 8, v144
	v_lshlrev_b32_e32 v139, 13, v138
	v_lshl_add_u32 v139, v140, 2, v139
	global_load_dwordx4 v[164:167], v139, s[74:75]
	global_load_dwordx4 v[168:171], v139, s[74:75] offset:16
	global_load_dwordx4 v[172:175], v139, s[74:75] offset:512
	global_load_dwordx4 v[176:179], v139, s[74:75] offset:528
	v_add_u32_e32 v199, 0x20000, v139
	global_load_dwordx4 v[182:185], v199, s[74:75]
	global_load_dwordx4 v[186:189], v199, s[74:75] offset:16
	global_load_dwordx4 v[190:193], v199, s[74:75] offset:512
	global_load_dwordx4 v[194:197], v199, s[74:75] offset:528
	v_add_u32_e32 v199, 0x40000, v139
	global_load_dwordx4 v[214:217], v199, s[74:75]
	global_load_dwordx4 v[218:221], v199, s[74:75] offset:16
	global_load_dwordx4 v[222:225], v199, s[74:75] offset:512
	global_load_dwordx4 v[226:229], v199, s[74:75] offset:528
	v_add_u32_e32 v199, 0x60000, v139
	global_load_dwordx4 v[146:149], v199, s[74:75]
	global_load_dwordx4 v[150:153], v199, s[74:75] offset:16
	global_load_dwordx4 v[154:157], v199, s[74:75] offset:512
	global_load_dwordx4 v[158:161], v199, s[74:75] offset:528
	v_lshrrev_b32_e32 v141, 1, v139
	v_lshlrev_b32_e32 v162, 2, v138
	v_xor_b32_e32 v163, 16, v208
	v_xor_b32_e32 v198, 32, v208
	v_lshlrev_b32_e32 v163, 2, v163
	v_lshlrev_b32_e32 v198, 2, v198
	s_waitcnt vmcnt(12)
	v_pk_add_f32 v[124:125], v[124:125], v[164:165]
	v_pk_add_f32 v[126:127], v[126:127], v[166:167]
	v_pk_add_f32 v[120:121], v[120:121], v[168:169]
	v_pk_add_f32 v[122:123], v[122:123], v[170:171]
	v_pk_add_f32 v[116:117], v[116:117], v[172:173]
	v_pk_add_f32 v[118:119], v[118:119], v[174:175]
	v_pk_add_f32 v[112:113], v[112:113], v[176:177]
	v_pk_add_f32 v[114:115], v[114:115], v[178:179]
	global_store_dwordx4 v139, v[124:127], s[58:59] sc1
	global_store_dwordx4 v139, v[120:123], s[58:59] offset:16 sc1
	global_store_dwordx4 v139, v[116:119], s[58:59] offset:512 sc1
	global_store_dwordx4 v139, v[112:115], s[58:59] offset:528 sc1
	v_cvt_pk_bf16_f32 v164, v124, v125
	v_cvt_pk_bf16_f32 v165, v126, v127
	v_cvt_pk_bf16_f32 v166, v120, v121
	v_cvt_pk_bf16_f32 v167, v122, v123
	v_cvt_pk_bf16_f32 v172, v116, v117
	v_cvt_pk_bf16_f32 v173, v118, v119
	v_cvt_pk_bf16_f32 v174, v112, v113
	v_cvt_pk_bf16_f32 v175, v114, v115
	global_store_dwordx4 v141, v[164:167], s[4:5] sc1
	global_store_dwordx4 v141, v[172:175], s[4:5] offset:256 sc1
	v_add_u32_e32 v199, 0x100000, v139
	global_load_dwordx4 v[164:167], v199, s[74:75]
	global_load_dwordx4 v[168:171], v199, s[74:75] offset:16
	global_load_dwordx4 v[172:175], v199, s[74:75] offset:512
	global_load_dwordx4 v[176:179], v199, s[74:75] offset:528
	v_mul_f32_e32 v230, v124, v124
	v_mul_f32_e32 v231, v120, v120
	v_mul_f32_e32 v232, v116, v116
	v_mul_f32_e32 v233, v112, v112
	v_fmac_f32_e32 v230, v125, v125
	v_fmac_f32_e32 v231, v121, v121
	v_fmac_f32_e32 v232, v117, v117
	v_fmac_f32_e32 v233, v113, v113
	v_fmac_f32_e32 v230, v126, v126
	v_fmac_f32_e32 v231, v122, v122
	v_fmac_f32_e32 v232, v118, v118
	v_fmac_f32_e32 v233, v114, v114
	v_fmac_f32_e32 v230, v127, v127
	v_fmac_f32_e32 v231, v123, v123
	v_fmac_f32_e32 v232, v119, v119
	v_fmac_f32_e32 v233, v115, v115
	v_add_f32_e32 v230, v230, v231
	v_add_f32_e32 v232, v232, v233
	v_add_f32_e32 v230, v230, v232
	ds_bpermute_b32 v231, v163, v230
	s_waitcnt lgkmcnt(0)
	v_add_f32_e32 v230, v230, v231
	ds_bpermute_b32 v231, v198, v230
	s_waitcnt lgkmcnt(0)
	v_add_f32_e32 v230, v230, v231
	s_and_saveexec_b64 s[26:27], s[38:39]
	s_nop 1
	global_atomic_add_f32 v162, v230, s[64:65]
	s_or_b64 exec, exec, s[26:27]
	s_waitcnt vmcnt(19)
	v_pk_add_f32 v[108:109], v[108:109], v[182:183]
	v_pk_add_f32 v[110:111], v[110:111], v[184:185]
	v_pk_add_f32 v[104:105], v[104:105], v[186:187]
	v_pk_add_f32 v[106:107], v[106:107], v[188:189]
	v_pk_add_f32 v[100:101], v[100:101], v[190:191]
	v_pk_add_f32 v[102:103], v[102:103], v[192:193]
	v_pk_add_f32 v[96:97], v[96:97], v[194:195]
	v_pk_add_f32 v[98:99], v[98:99], v[196:197]
	v_add_u32_e32 v200, 0x20000, v139
	global_store_dwordx4 v200, v[108:111], s[58:59] sc1
	global_store_dwordx4 v200, v[104:107], s[58:59] offset:16 sc1
	global_store_dwordx4 v200, v[100:103], s[58:59] offset:512 sc1
	global_store_dwordx4 v200, v[96:99], s[58:59] offset:528 sc1
	v_cvt_pk_bf16_f32 v182, v108, v109
	v_cvt_pk_bf16_f32 v183, v110, v111
	v_cvt_pk_bf16_f32 v184, v104, v105
	v_cvt_pk_bf16_f32 v185, v106, v107
	v_cvt_pk_bf16_f32 v190, v100, v101
	v_cvt_pk_bf16_f32 v191, v102, v103
	v_cvt_pk_bf16_f32 v192, v96, v97
	v_cvt_pk_bf16_f32 v193, v98, v99
	v_add_u32_e32 v201, 0x10000, v141
	global_store_dwordx4 v201, v[182:185], s[4:5] sc1
	global_store_dwordx4 v201, v[190:193], s[4:5] offset:256 sc1
	v_add_u32_e32 v199, 0x120000, v139
	global_load_dwordx4 v[182:185], v199, s[74:75]
	global_load_dwordx4 v[186:189], v199, s[74:75] offset:16
	global_load_dwordx4 v[190:193], v199, s[74:75] offset:512
	global_load_dwordx4 v[194:197], v199, s[74:75] offset:528
	v_mul_f32_e32 v230, v108, v108
	v_mul_f32_e32 v231, v104, v104
	v_mul_f32_e32 v232, v100, v100
	v_mul_f32_e32 v233, v96, v96
	v_fmac_f32_e32 v230, v109, v109
	v_fmac_f32_e32 v231, v105, v105
	v_fmac_f32_e32 v232, v101, v101
	v_fmac_f32_e32 v233, v97, v97
	v_fmac_f32_e32 v230, v110, v110
	v_fmac_f32_e32 v231, v106, v106
	v_fmac_f32_e32 v232, v102, v102
	v_fmac_f32_e32 v233, v98, v98
	v_fmac_f32_e32 v230, v111, v111
	v_fmac_f32_e32 v231, v107, v107
	v_fmac_f32_e32 v232, v103, v103
	v_fmac_f32_e32 v233, v99, v99
	v_add_f32_e32 v230, v230, v231
	v_add_f32_e32 v232, v232, v233
	v_add_f32_e32 v230, v230, v232
	ds_bpermute_b32 v231, v163, v230
	s_waitcnt lgkmcnt(0)
; __device__ __forceinline__ float bflo(unsigned u) { return __uint_as_float(u << 16); }
;     __device__ __forceinline__ void operator()(const f32x4 (&acc)[2][2][4][2], const pg8::Unit& u, int wr, int wc, int fr, int fq) const {
;     ...
;         for (int ai = 0; ai < 2; ++ai)
; #pragma unroll
;             for (int m = 0; m < 4; ++m) {
;                 const int row = u.pm * 256 + ai * 128 + wr * 64 + m * 16 + fr;
;                 const size_t off = (size_t)row * DM + col0;
;                 bf16_t* hrow = (hb_hi && row >= HALF_TOK) ? hb_hi + (size_t)(row - HALF_TOK) * DM + col0 : hb + off;
;                 float rs = 0.f, part = 0.f;
;                 if (MODE == 1) rs = rsqrtf(ssq_in[row] * (1.f / DM) + EPS);
; #pragma unroll
;                 for (int bj = 0; bj < 2; ++bj) {
;                     const size_t o = off + bj * 128;
;                     const f32x4 bs0 = *(const f32x4*)(base + o), bs1 = *(const f32x4*)(base + o + 4);
;                     f32x4 a0 = acc[ai][bj][m][0], a1 = acc[ai][bj][m][1];
;                     if (MODE == 1) {
;                         const u32x4 pw = *(const u32x4*)(pp + o);
;                         a0[0] = bflo(pw.x) * sigmoidf_(rs * a0[0]); a0[1] = bfhi(pw.x) * sigmoidf_(rs * a0[1]);
;                         a0[2] = bflo(pw.y) * sigmoidf_(rs * a0[2]); a0[3] = bfhi(pw.y) * sigmoidf_(rs * a0[3]);
;                         a1[0] = bflo(pw.z) * sigmoidf_(rs * a1[0]); a1[1] = bfhi(pw.z) * sigmoidf_(rs * a1[1]);
;                         a1[2] = bflo(pw.w) * sigmoidf_(rs * a1[2]); a1[3] = bfhi(pw.w) * sigmoidf_(rs * a1[3]);
;                     }
;                     const f32x4 v0 = bs0 + a0, v1 = bs1 + a1;
;                     *(f32x4*)(out + o) = v0; *(f32x4*)(out + o + 4) = v1;
;                     if (wr_hb) {
;                         const u32x2 h0 = pack4(v0), h1 = pack4(v1); const u32x4 hw = {h0.x, h0.y, h1.x, h1.y};
;                         *(u32x4*)(hrow + bj * 128) = hw;
;                         part += ((v0[0] * v0[0] + v0[1] * v0[1]) + (v0[2] * v0[2] + v0[3] * v0[3])) + ((v1[0] * v1[0] + v1[1] * v1[1]) + (v1[2] * v1[2] + v1[3] * v1[3]));
;                     }
;                 }
;                 if (wr_hb) { part += __shfl_xor(part, 16); part += __shfl_xor(part, 32); if (fq == 0) unsafeAtomicAdd(ssq_out + row, part); }
	v_add_f32_e32 v230, v230, v231
	ds_bpermute_b32 v231, v198, v230
	s_waitcnt lgkmcnt(0)
	v_add_f32_e32 v230, v230, v231
	s_and_saveexec_b64 s[26:27], s[38:39]
	s_nop 1
	global_atomic_add_f32 v162, v230, s[64:65] offset:64
	s_or_b64 exec, exec, s[26:27]
	s_waitcnt vmcnt(26)
	v_pk_add_f32 v[92:93], v[92:93], v[214:215]
	v_pk_add_f32 v[94:95], v[94:95], v[216:217]
	v_pk_add_f32 v[88:89], v[88:89], v[218:219]
	v_pk_add_f32 v[90:91], v[90:91], v[220:221]
	v_pk_add_f32 v[84:85], v[84:85], v[222:223]
	v_pk_add_f32 v[86:87], v[86:87], v[224:225]
	v_pk_add_f32 v[80:81], v[80:81], v[226:227]
	v_pk_add_f32 v[82:83], v[82:83], v[228:229]
	v_add_u32_e32 v200, 0x40000, v139
	global_store_dwordx4 v200, v[92:95], s[58:59] sc1
	global_store_dwordx4 v200, v[88:91], s[58:59] offset:16 sc1
	global_store_dwordx4 v200, v[84:87], s[58:59] offset:512 sc1
	global_store_dwordx4 v200, v[80:83], s[58:59] offset:528 sc1
	v_cvt_pk_bf16_f32 v214, v92, v93
	v_cvt_pk_bf16_f32 v215, v94, v95
	v_cvt_pk_bf16_f32 v216, v88, v89
	v_cvt_pk_bf16_f32 v217, v90, v91
	v_cvt_pk_bf16_f32 v222, v84, v85
	v_cvt_pk_bf16_f32 v223, v86, v87
	v_cvt_pk_bf16_f32 v224, v80, v81
	v_cvt_pk_bf16_f32 v225, v82, v83
	v_add_u32_e32 v201, 0x20000, v141
	global_store_dwordx4 v201, v[214:217], s[4:5] sc1
	global_store_dwordx4 v201, v[222:225], s[4:5] offset:256 sc1
	v_add_u32_e32 v199, 0x140000, v139
	global_load_dwordx4 v[214:217], v199, s[74:75]
	global_load_dwordx4 v[218:221], v199, s[74:75] offset:16
	global_load_dwordx4 v[222:225], v199, s[74:75] offset:512
	global_load_dwordx4 v[226:229], v199, s[74:75] offset:528
	v_mul_f32_e32 v230, v92, v92
	v_mul_f32_e32 v231, v88, v88
	v_mul_f32_e32 v232, v84, v84
	v_mul_f32_e32 v233, v80, v80
	v_fmac_f32_e32 v230, v93, v93
	v_fmac_f32_e32 v231, v89, v89
	v_fmac_f32_e32 v232, v85, v85
	v_fmac_f32_e32 v233, v81, v81
	v_fmac_f32_e32 v230, v94, v94
	v_fmac_f32_e32 v231, v90, v90
	v_fmac_f32_e32 v232, v86, v86
	v_fmac_f32_e32 v233, v82, v82
	v_fmac_f32_e32 v230, v95, v95
	v_fmac_f32_e32 v231, v91, v91
	v_fmac_f32_e32 v232, v87, v87
	v_fmac_f32_e32 v233, v83, v83
	v_add_f32_e32 v230, v230, v231
	v_add_f32_e32 v232, v232, v233
	v_add_f32_e32 v230, v230, v232
	ds_bpermute_b32 v231, v163, v230
	s_waitcnt lgkmcnt(0)
	v_add_f32_e32 v230, v230, v231
	ds_bpermute_b32 v231, v198, v230
	s_waitcnt lgkmcnt(0)
	v_add_f32_e32 v230, v230, v231
	s_and_saveexec_b64 s[26:27], s[38:39]
	s_nop 1
	global_atomic_add_f32 v162, v230, s[64:65] offset:128
	s_or_b64 exec, exec, s[26:27]
	s_waitcnt vmcnt(33)
	v_pk_add_f32 v[76:77], v[76:77], v[146:147]
	v_pk_add_f32 v[78:79], v[78:79], v[148:149]
	v_pk_add_f32 v[72:73], v[72:73], v[150:151]
	v_pk_add_f32 v[74:75], v[74:75], v[152:153]
	v_pk_add_f32 v[68:69], v[68:69], v[154:155]
	v_pk_add_f32 v[70:71], v[70:71], v[156:157]
	v_pk_add_f32 v[64:65], v[64:65], v[158:159]
	v_pk_add_f32 v[66:67], v[66:67], v[160:161]
	v_add_u32_e32 v200, 0x60000, v139
	global_store_dwordx4 v200, v[76:79], s[58:59] sc1
	global_store_dwordx4 v200, v[72:75], s[58:59] offset:16 sc1
	global_store_dwordx4 v200, v[68:71], s[58:59] offset:512 sc1
	global_store_dwordx4 v200, v[64:67], s[58:59] offset:528 sc1
	v_cvt_pk_bf16_f32 v146, v76, v77
	v_cvt_pk_bf16_f32 v147, v78, v79
	v_cvt_pk_bf16_f32 v148, v72, v73
	v_cvt_pk_bf16_f32 v149, v74, v75
	v_cvt_pk_bf16_f32 v154, v68, v69
	v_cvt_pk_bf16_f32 v155, v70, v71
	v_cvt_pk_bf16_f32 v156, v64, v65
	v_cvt_pk_bf16_f32 v157, v66, v67
	v_add_u32_e32 v201, 0x30000, v141
	global_store_dwordx4 v201, v[146:149], s[4:5] sc1
	global_store_dwordx4 v201, v[154:157], s[4:5] offset:256 sc1
	v_add_u32_e32 v199, 0x160000, v139
	global_load_dwordx4 v[146:149], v199, s[74:75]
	global_load_dwordx4 v[150:153], v199, s[74:75] offset:16
	global_load_dwordx4 v[154:157], v199, s[74:75] offset:512
	global_load_dwordx4 v[158:161], v199, s[74:75] offset:528
	v_mul_f32_e32 v230, v76, v76
	v_mul_f32_e32 v231, v72, v72
	v_mul_f32_e32 v232, v68, v68
	v_mul_f32_e32 v233, v64, v64
	v_fmac_f32_e32 v230, v77, v77
	v_fmac_f32_e32 v231, v73, v73
	v_fmac_f32_e32 v232, v69, v69
	v_fmac_f32_e32 v233, v65, v65
	v_fmac_f32_e32 v230, v78, v78
	v_fmac_f32_e32 v231, v74, v74
	v_fmac_f32_e32 v232, v70, v70
	v_fmac_f32_e32 v233, v66, v66
	v_fmac_f32_e32 v230, v79, v79
	v_fmac_f32_e32 v231, v75, v75
	v_fmac_f32_e32 v232, v71, v71
	v_fmac_f32_e32 v233, v67, v67
	v_add_f32_e32 v230, v230, v231
	v_add_f32_e32 v232, v232, v233
	v_add_f32_e32 v230, v230, v232
	ds_bpermute_b32 v231, v163, v230
	s_waitcnt lgkmcnt(0)
	v_add_f32_e32 v230, v230, v231
	ds_bpermute_b32 v231, v198, v230
	s_waitcnt lgkmcnt(0)
	v_add_f32_e32 v230, v230, v231
	s_and_saveexec_b64 s[26:27], s[38:39]
	s_nop 1
	global_atomic_add_f32 v162, v230, s[64:65] offset:192
	s_or_b64 exec, exec, s[26:27]
	s_waitcnt vmcnt(34)
	v_pk_add_f32 v[60:61], v[60:61], v[164:165]
	v_pk_add_f32 v[62:63], v[62:63], v[166:167]
	v_pk_add_f32 v[56:57], v[56:57], v[168:169]
	v_pk_add_f32 v[58:59], v[58:59], v[170:171]
	v_pk_add_f32 v[52:53], v[52:53], v[172:173]
	v_pk_add_f32 v[54:55], v[54:55], v[174:175]
	v_pk_add_f32 v[48:49], v[48:49], v[176:177]
	v_pk_add_f32 v[50:51], v[50:51], v[178:179]
	v_add_u32_e32 v200, 0x100000, v139
	global_store_dwordx4 v200, v[60:63], s[58:59] sc1
	global_store_dwordx4 v200, v[56:59], s[58:59] offset:16 sc1
	global_store_dwordx4 v200, v[52:55], s[58:59] offset:512 sc1
	global_store_dwordx4 v200, v[48:51], s[58:59] offset:528 sc1
	v_cvt_pk_bf16_f32 v164, v60, v61
	v_cvt_pk_bf16_f32 v165, v62, v63
	v_cvt_pk_bf16_f32 v166, v56, v57
	v_cvt_pk_bf16_f32 v167, v58, v59
	v_cvt_pk_bf16_f32 v172, v52, v53
	v_cvt_pk_bf16_f32 v173, v54, v55
	v_cvt_pk_bf16_f32 v174, v48, v49
	v_cvt_pk_bf16_f32 v175, v50, v51
	v_add_u32_e32 v201, 0x80000, v141
	global_store_dwordx4 v201, v[164:167], s[4:5] sc1
	global_store_dwordx4 v201, v[172:175], s[4:5] offset:256 sc1
	v_mul_f32_e32 v230, v60, v60
	v_mul_f32_e32 v231, v56, v56
	v_mul_f32_e32 v232, v52, v52
	v_mul_f32_e32 v233, v48, v48
	v_fmac_f32_e32 v230, v61, v61
	v_fmac_f32_e32 v231, v57, v57
	v_fmac_f32_e32 v232, v53, v53
	v_fmac_f32_e32 v233, v49, v49
	v_fmac_f32_e32 v230, v62, v62
	v_fmac_f32_e32 v231, v58, v58
	v_fmac_f32_e32 v232, v54, v54
	v_fmac_f32_e32 v233, v50, v50
	v_fmac_f32_e32 v230, v63, v63
	v_fmac_f32_e32 v231, v59, v59
	v_fmac_f32_e32 v232, v55, v55
	v_fmac_f32_e32 v233, v51, v51
	v_add_f32_e32 v230, v230, v231
	v_add_f32_e32 v232, v232, v233
	v_add_f32_e32 v230, v230, v232
	ds_bpermute_b32 v231, v163, v230
	s_waitcnt lgkmcnt(0)
; __device__ __forceinline__ float bflo(unsigned u) { return __uint_as_float(u << 16); }
;     __device__ __forceinline__ void operator()(const f32x4 (&acc)[2][2][4][2], const pg8::Unit& u, int wr, int wc, int fr, int fq) const {
;     ...
;         for (int ai = 0; ai < 2; ++ai)
; #pragma unroll
;             for (int m = 0; m < 4; ++m) {
;                 const int row = u.pm * 256 + ai * 128 + wr * 64 + m * 16 + fr;
;                 const size_t off = (size_t)row * DM + col0;
;                 bf16_t* hrow = (hb_hi && row >= HALF_TOK) ? hb_hi + (size_t)(row - HALF_TOK) * DM + col0 : hb + off;
;                 float rs = 0.f, part = 0.f;
;                 if (MODE == 1) rs = rsqrtf(ssq_in[row] * (1.f / DM) + EPS);
; #pragma unroll
;                 for (int bj = 0; bj < 2; ++bj) {
;                     const size_t o = off + bj * 128;
;                     const f32x4 bs0 = *(const f32x4*)(base + o), bs1 = *(const f32x4*)(base + o + 4);
;                     f32x4 a0 = acc[ai][bj][m][0], a1 = acc[ai][bj][m][1];
;                     if (MODE == 1) {
;                         const u32x4 pw = *(const u32x4*)(pp + o);
;                         a0[0] = bflo(pw.x) * sigmoidf_(rs * a0[0]); a0[1] = bfhi(pw.x) * sigmoidf_(rs * a0[1]);
;                         a0[2] = bflo(pw.y) * sigmoidf_(rs * a0[2]); a0[3] = bfhi(pw.y) * sigmoidf_(rs * a0[3]);
;                         a1[0] = bflo(pw.z) * sigmoidf_(rs * a1[0]); a1[1] = bfhi(pw.z) * sigmoidf_(rs * a1[1]);
;                         a1[2] = bflo(pw.w) * sigmoidf_(rs * a1[2]); a1[3] = bfhi(pw.w) * sigmoidf_(rs * a1[3]);
;                     }
;                     const f32x4 v0 = bs0 + a0, v1 = bs1 + a1;
;                     *(f32x4*)(out + o) = v0; *(f32x4*)(out + o + 4) = v1;
;                     if (wr_hb) {
;                         const u32x2 h0 = pack4(v0), h1 = pack4(v1); const u32x4 hw = {h0.x, h0.y, h1.x, h1.y};
;                         *(u32x4*)(hrow + bj * 128) = hw;
;                         part += ((v0[0] * v0[0] + v0[1] * v0[1]) + (v0[2] * v0[2] + v0[3] * v0[3])) + ((v1[0] * v1[0] + v1[1] * v1[1]) + (v1[2] * v1[2] + v1[3] * v1[3]));
;                     }
;                 }
;                 if (wr_hb) { part += __shfl_xor(part, 16); part += __shfl_xor(part, 32); if (fq == 0) unsafeAtomicAdd(ssq_out + row, part); }
	v_add_f32_e32 v230, v230, v231
	ds_bpermute_b32 v231, v198, v230
	s_waitcnt lgkmcnt(0)
	v_add_f32_e32 v230, v230, v231
	s_and_saveexec_b64 s[26:27], s[38:39]
	s_nop 1
	global_atomic_add_f32 v162, v230, s[64:65] offset:512
	s_or_b64 exec, exec, s[26:27]
	s_waitcnt vmcnt(30)
	v_pk_add_f32 v[44:45], v[44:45], v[182:183]
	v_pk_add_f32 v[46:47], v[46:47], v[184:185]
	v_pk_add_f32 v[40:41], v[40:41], v[186:187]
	v_pk_add_f32 v[42:43], v[42:43], v[188:189]
	v_pk_add_f32 v[36:37], v[36:37], v[190:191]
	v_pk_add_f32 v[38:39], v[38:39], v[192:193]
	v_pk_add_f32 v[32:33], v[32:33], v[194:195]
	v_pk_add_f32 v[34:35], v[34:35], v[196:197]
	v_add_u32_e32 v200, 0x120000, v139
	global_store_dwordx4 v200, v[44:47], s[58:59] sc1
	global_store_dwordx4 v200, v[40:43], s[58:59] offset:16 sc1
	global_store_dwordx4 v200, v[36:39], s[58:59] offset:512 sc1
	global_store_dwordx4 v200, v[32:35], s[58:59] offset:528 sc1
	v_cvt_pk_bf16_f32 v182, v44, v45
	v_cvt_pk_bf16_f32 v183, v46, v47
	v_cvt_pk_bf16_f32 v184, v40, v41
	v_cvt_pk_bf16_f32 v185, v42, v43
	v_cvt_pk_bf16_f32 v190, v36, v37
	v_cvt_pk_bf16_f32 v191, v38, v39
	v_cvt_pk_bf16_f32 v192, v32, v33
	v_cvt_pk_bf16_f32 v193, v34, v35
	v_add_u32_e32 v201, 0x90000, v141
	global_store_dwordx4 v201, v[182:185], s[4:5] sc1
	global_store_dwordx4 v201, v[190:193], s[4:5] offset:256 sc1
	v_mul_f32_e32 v230, v44, v44
	v_mul_f32_e32 v231, v40, v40
	v_mul_f32_e32 v232, v36, v36
	v_mul_f32_e32 v233, v32, v32
	v_fmac_f32_e32 v230, v45, v45
	v_fmac_f32_e32 v231, v41, v41
	v_fmac_f32_e32 v232, v37, v37
	v_fmac_f32_e32 v233, v33, v33
	v_fmac_f32_e32 v230, v46, v46
	v_fmac_f32_e32 v231, v42, v42
	v_fmac_f32_e32 v232, v38, v38
	v_fmac_f32_e32 v233, v34, v34
	v_fmac_f32_e32 v230, v47, v47
	v_fmac_f32_e32 v231, v43, v43
	v_fmac_f32_e32 v232, v39, v39
	v_fmac_f32_e32 v233, v35, v35
	v_add_f32_e32 v230, v230, v231
	v_add_f32_e32 v232, v232, v233
	v_add_f32_e32 v230, v230, v232
	ds_bpermute_b32 v231, v163, v230
	s_waitcnt lgkmcnt(0)
	v_add_f32_e32 v230, v230, v231
	ds_bpermute_b32 v231, v198, v230
	s_waitcnt lgkmcnt(0)
	v_add_f32_e32 v230, v230, v231
	s_and_saveexec_b64 s[26:27], s[38:39]
	s_nop 1
	global_atomic_add_f32 v162, v230, s[64:65] offset:576
	s_or_b64 exec, exec, s[26:27]
	s_waitcnt vmcnt(26)
	v_pk_add_f32 v[28:29], v[28:29], v[214:215]
	v_pk_add_f32 v[30:31], v[30:31], v[216:217]
	v_pk_add_f32 v[24:25], v[24:25], v[218:219]
	v_pk_add_f32 v[26:27], v[26:27], v[220:221]
	v_pk_add_f32 v[20:21], v[20:21], v[222:223]
	v_pk_add_f32 v[22:23], v[22:23], v[224:225]
	v_pk_add_f32 v[16:17], v[16:17], v[226:227]
	v_pk_add_f32 v[18:19], v[18:19], v[228:229]
	v_add_u32_e32 v200, 0x140000, v139
	global_store_dwordx4 v200, v[28:31], s[58:59] sc1
	global_store_dwordx4 v200, v[24:27], s[58:59] offset:16 sc1
	global_store_dwordx4 v200, v[20:23], s[58:59] offset:512 sc1
	global_store_dwordx4 v200, v[16:19], s[58:59] offset:528 sc1
	v_cvt_pk_bf16_f32 v214, v28, v29
	v_cvt_pk_bf16_f32 v215, v30, v31
	v_cvt_pk_bf16_f32 v216, v24, v25
	v_cvt_pk_bf16_f32 v217, v26, v27
	v_cvt_pk_bf16_f32 v222, v20, v21
	v_cvt_pk_bf16_f32 v223, v22, v23
	v_cvt_pk_bf16_f32 v224, v16, v17
	v_cvt_pk_bf16_f32 v225, v18, v19
	v_add_u32_e32 v201, 0xa0000, v141
	global_store_dwordx4 v201, v[214:217], s[4:5] sc1
	global_store_dwordx4 v201, v[222:225], s[4:5] offset:256 sc1
	v_mul_f32_e32 v230, v28, v28
	v_mul_f32_e32 v231, v24, v24
	v_mul_f32_e32 v232, v20, v20
	v_mul_f32_e32 v233, v16, v16
	v_fmac_f32_e32 v230, v29, v29
	v_fmac_f32_e32 v231, v25, v25
	v_fmac_f32_e32 v232, v21, v21
	v_fmac_f32_e32 v233, v17, v17
	v_fmac_f32_e32 v230, v30, v30
	v_fmac_f32_e32 v231, v26, v26
	v_fmac_f32_e32 v232, v22, v22
	v_fmac_f32_e32 v233, v18, v18
	v_fmac_f32_e32 v230, v31, v31
	v_fmac_f32_e32 v231, v27, v27
	v_fmac_f32_e32 v232, v23, v23
	v_fmac_f32_e32 v233, v19, v19
	v_add_f32_e32 v230, v230, v231
	v_add_f32_e32 v232, v232, v233
	v_add_f32_e32 v230, v230, v232
	ds_bpermute_b32 v231, v163, v230
	s_waitcnt lgkmcnt(0)
	v_add_f32_e32 v230, v230, v231
	ds_bpermute_b32 v231, v198, v230
	s_waitcnt lgkmcnt(0)
	v_add_f32_e32 v230, v230, v231
	s_and_saveexec_b64 s[26:27], s[38:39]
	s_nop 1
	global_atomic_add_f32 v162, v230, s[64:65] offset:640
	s_or_b64 exec, exec, s[26:27]
	s_waitcnt vmcnt(22)
	v_pk_add_f32 v[12:13], v[12:13], v[146:147]
	v_pk_add_f32 v[14:15], v[14:15], v[148:149]
	v_pk_add_f32 v[8:9], v[8:9], v[150:151]
	v_pk_add_f32 v[10:11], v[10:11], v[152:153]
	v_pk_add_f32 v[4:5], v[4:5], v[154:155]
	v_pk_add_f32 v[6:7], v[6:7], v[156:157]
	v_pk_add_f32 v[0:1], v[0:1], v[158:159]
	v_pk_add_f32 v[2:3], v[2:3], v[160:161]
	v_add_u32_e32 v200, 0x160000, v139
	global_store_dwordx4 v200, v[12:15], s[58:59] sc1
	global_store_dwordx4 v200, v[8:11], s[58:59] offset:16 sc1
	global_store_dwordx4 v200, v[4:7], s[58:59] offset:512 sc1
	global_store_dwordx4 v200, v[0:3], s[58:59] offset:528 sc1
	v_cvt_pk_bf16_f32 v146, v12, v13
	v_cvt_pk_bf16_f32 v147, v14, v15
	v_cvt_pk_bf16_f32 v148, v8, v9
	v_cvt_pk_bf16_f32 v149, v10, v11
	v_cvt_pk_bf16_f32 v154, v4, v5
	v_cvt_pk_bf16_f32 v155, v6, v7
	v_cvt_pk_bf16_f32 v156, v0, v1
	v_cvt_pk_bf16_f32 v157, v2, v3
	v_add_u32_e32 v201, 0xb0000, v141
	global_store_dwordx4 v201, v[146:149], s[4:5] sc1
	global_store_dwordx4 v201, v[154:157], s[4:5] offset:256 sc1
	v_mul_f32_e32 v230, v12, v12
	v_mul_f32_e32 v231, v8, v8
	v_mul_f32_e32 v232, v4, v4
	v_mul_f32_e32 v233, v0, v0
	v_fmac_f32_e32 v230, v13, v13
	v_fmac_f32_e32 v231, v9, v9
	v_fmac_f32_e32 v232, v5, v5
	v_fmac_f32_e32 v233, v1, v1
	v_fmac_f32_e32 v230, v14, v14
	v_fmac_f32_e32 v231, v10, v10
	v_fmac_f32_e32 v232, v6, v6
	v_fmac_f32_e32 v233, v2, v2
	v_fmac_f32_e32 v230, v15, v15
	v_fmac_f32_e32 v231, v11, v11
	v_fmac_f32_e32 v232, v7, v7
	v_fmac_f32_e32 v233, v3, v3
	v_add_f32_e32 v230, v230, v231
	v_add_f32_e32 v232, v232, v233
	v_add_f32_e32 v230, v230, v232
	ds_bpermute_b32 v231, v163, v230
	s_waitcnt lgkmcnt(0)
	v_add_f32_e32 v230, v230, v231
	ds_bpermute_b32 v231, v198, v230
	s_waitcnt lgkmcnt(0)
	v_add_f32_e32 v230, v230, v231
	s_and_saveexec_b64 s[26:27], s[38:39]
	s_nop 1
	global_atomic_add_f32 v162, v230, s[64:65] offset:704
	s_or_b64 exec, exec, s[26:27]
